# removed the cooperative-groups grid sync at kernel start (the first XCD grid barrier already waits for the workgroup census)
# speedup vs baseline: 1.0145x; 1.0049x over previous
; #define LAS __attribute__((address_space(3)))
; #define MYTID() pg8::pg8_tid(lds)
; __device__ __forceinline__ void prologue(const Params& p, LAS unsigned char* lds, int tid, int lane, int wave) {
;     LAS float* scr = (LAS float*)(lds + wave * 16384);
;     const int gw = blockIdx.x * 8 + wave, NGW = gridDim.x * 8;
;     constexpr int I_IN = (DM / 64) * (DIN / 32), I_OUT = (DM / 64) * (DM / 32), I_G = (DM / 64) * (DFF / 32), I_DN = (DFF / 64) * (DM / 32);
;     constexpr int I_LAYER = I_IN + I_OUT + 2 * I_G + I_DN;
;     bf16_t* WIN = (bf16_t*)(p.ws + WS_WIN); bf16_t* WOUT = (bf16_t*)(p.ws + WS_WOUT); bf16_t* WGU = (bf16_t*)(p.ws + WS_WGU); bf16_t* WDN = (bf16_t*)(p.ws + WS_WDN);
;     for (int it = gw; it < 2 * I_LAYER; it += NGW) {
;         const int l = it / I_LAYER; int r = it % I_LAYER;
;         if (r < I_IN) { const int nb = DIN / 32, k0 = 64 * (r / nb), n0 = 32 * (r % nb); const int seg = n0 >> 8, off = n0 & 255, hi = off >> 7, lo = off & 127;
;             const int drow = (seg == 0) ? off : (seg == 1) ? 256 * (1 + hi) + lo : (seg == 2) ? 256 * (1 + hi) + 128 + lo : (seg == 3) ? 256 * (3 + hi) + lo : (seg == 5) ? 256 * (3 + hi) + 128 + lo : (seg == 4) ? 256 * 5 + off : 256 * seg + off;
;             transpose_item(p.w_in + (size_t)l * DM * DIN, p.g_mix + l * DM, DM, DIN, WIN + (size_t)l * DIN * DM, drow, scr, k0, n0, lane); continue; } r -= I_IN;
; __global__ void __launch_bounds__(512, 2) fwd_megakernel(Params p) {
;     ...
;     { const int tid0 = threadIdx.x; volatile LAS unsigned* stw = (volatile LAS unsigned*)(lds + 131072); if (tid0 < 64) stw[tid0] = 0u;
;       if (tid0 < 8) ((volatile LAS int*)(lds + LDS_RC + 4096))[tid0] = 0;
;       if ((tid0 & 63) == 0) ((volatile LAS int*)(lds + 131072 + 256))[(int)__builtin_amdgcn_s_getreg((5 << 11) | 4) & 63] = tid0 >> 6; }
;     __syncthreads();
;     XcdBarrier bar = xcd_barrier_post((unsigned*)(p.ws + WS_CTL), (volatile LAS unsigned*)(lds + 131072));
;     cg::this_grid().sync();
;     { const int t_ = MYTID(); prologue(p, lds, t_, t_ & 63, t_ >> 6); convert_rows(p, t_ & 63, bx * 8 + (t_ >> 6), G * 8, MP, MT); }
.LBB0_9:
	s_or_b64 exec, exec, s[6:7]
	s_load_dwordx2 s[6:7], s[4:5], 0x4
	v_lshrrev_b32_e32 v2, 20, v0
	v_lshrrev_b32_e32 v0, 10, v0
	v_or_b32_e32 v0, v0, v2
	s_movk_i32 s3, 0x3ff
	s_waitcnt lgkmcnt(0)
	v_writelane_b32 v254, s6, 1
	v_and_or_b32 v0, v0, s3, v1
	v_cmp_eq_u32_e32 vcc, 0, v0
	v_writelane_b32 v254, s7, 2
	s_barrier
	s_load_dwordx16 s[12:27], s[0:1], 0x0
	s_load_dwordx16 s[60:75], s[0:1], 0x40
	s_barrier
	s_waitcnt lgkmcnt(0)
	s_getreg_b32 s0, hwreg(HW_REG_HW_ID, 0, 6)
	s_and_b32 s0, s0, 63
	s_lshl_b32 s0, s0, 2
	s_add_i32 s0, s0, 0
	s_add_i32 s0, s0, 0x20100
	v_mov_b32_e32 v0, s0
	ds_read_b32 v0, v0
	v_mbcnt_lo_u32_b32 v1, -1, 0
	v_mbcnt_hi_u32_b32 v190, -1, v1
	s_lshl_b32 s4, s2, 3
	v_and_b32_e32 v128, 63, v190
	s_waitcnt lgkmcnt(0)
	v_readfirstlane_b32 s0, v0
	v_lshlrev_b32_e32 v130, 3, v128
	s_nop 0
	v_lshl_add_u32 v31, s0, 6, v190
	s_mov_b32 s0, s4
	v_writelane_b32 v254, s0, 3
	v_ashrrev_i32_e32 v0, 6, v31
	v_add_u32_e32 v30, s4, v0
	v_writelane_b32 v254, s1, 4
	s_lshl_b32 s0, s33, 3
	v_writelane_b32 v254, s0, 5
	s_movk_i32 s0, 0x2d00
	v_cmp_gt_i32_e32 vcc, s0, v30
	s_and_saveexec_b64 s[4:5], vcc
	s_cbranch_execz .LBB0_158
	v_lshrrev_b32_e32 v34, 3, v128
	v_and_b32_e32 v4, 56, v130
	v_lshl_add_u32 v1, v0, 14, 0
	v_lshrrev_b32_e32 v0, 5, v128
	v_and_b32_e32 v2, 31, v190
	v_mul_u32_u24_e32 v5, 0x84, v4
	v_lshlrev_b32_e32 v6, 2, v34
	v_lshl_add_u32 v32, v2, 2, v1
	s_movk_i32 s0, 0x84
	v_add3_u32 v35, v1, v5, v6
	v_or_b32_e32 v1, 2, v0
	v_mov_b32_e32 v5, 0x108
	v_mad_u32_u24 v40, v1, s0, v5
	v_mov_b32_e32 v5, 0x318
	v_mad_u32_u24 v41, v1, s0, v5
	v_mov_b32_e32 v5, 0x528
	s_add_u32 s6, s58, 0x800000
	v_mad_u32_u24 v42, v1, s0, v5
	v_mov_b32_e32 v5, 0x738
	s_addc_u32 s7, s59, 0
	v_mad_u32_u24 v43, v1, s0, v5
	v_mov_b32_e32 v5, 0x948
	s_add_u32 s8, s58, 0xc00000
	v_mad_u32_u24 v44, v1, s0, v5
	v_mov_b32_e32 v5, 0xb58
	s_addc_u32 s9, s59, 0
	v_mad_u32_u24 v45, v1, s0, v5
	v_mov_b32_e32 v5, 0xd68
	s_add_u32 s10, s58, 0x2200000
	v_mad_u32_u24 v46, v1, s0, v5
	v_mov_b32_e32 v5, 0xf78
	s_addc_u32 s11, s59, 0
	v_mad_u32_u24 v47, v1, s0, v5
	v_mov_b32_e32 v5, 0x1188
	v_mad_u32_u24 v48, v1, s0, v5
	v_mov_b32_e32 v5, 0x1398
	s_add_u32 s30, s58, 0x34800000
	v_mad_u32_u24 v49, v1, s0, v5
	v_mov_b32_e32 v5, 0x15a8
	s_addc_u32 s31, s59, 0
	v_mad_u32_u24 v50, v1, s0, v5
	v_mov_b32_e32 v5, 0x17b8
	s_cmp_lg_u64 s[46:47], 0
	v_mov_b32_e32 v3, 0
	v_mad_u32_u24 v33, v0, s0, v32
	v_mad_u32_u24 v51, v1, s0, v5
	s_cselect_b64 s[34:35], -1, 0
	s_cmp_lg_u64 s[22:23], 0
	v_readlane_b32 s0, v254, 5
	v_mov_b32_e32 v5, 0x7ffff800
	v_or_b32_e32 v36, 8, v34
	v_or_b32_e32 v37, 16, v34
	v_or_b32_e32 v38, 24, v34
	v_mul_u32_u24_e32 v39, 0x84, v1
	s_cselect_b64 s[36:37], -1, 0
	v_mov_b32_e32 v1, v3
	v_lshlrev_b32_e32 v52, 5, v30
	s_lshl_b32 s3, s0, 5
	v_lshl_add_u32 v53, v30, 1, v5
	s_lshl_b32 s86, s0, 1
	s_mov_b32 s87, 0xb00000
	s_movk_i32 s88, 0x1600
	s_movk_i32 s89, 0xb00
	v_mov_b32_e32 v54, 0xfffffa80
	v_lshlrev_b32_e32 v2, 2, v2
	v_add_u32_e32 v55, 0x400, v33
	v_add_u32_e32 v56, 0x800, v33
	v_add_u32_e32 v57, 0xc00, v33
	v_add_u32_e32 v58, 0x1000, v33
	v_add_u32_e32 v59, 0x1400, v33
	v_add_u32_e32 v60, 0x1800, v33
	v_add_u32_e32 v61, 0x1c00, v33
	v_lshlrev_b32_e32 v4, 1, v4
	v_mov_b32_e32 v62, 5
	v_mov_b32_e32 v63, 3
	v_mov_b32_e32 v64, 6
	v_mov_b32_e32 v65, v30
	s_mov_b32 s90, 0x68000
	s_mov_b32 s91, 0x6e000
	s_mov_b32 s92, 0x73000
	s_mov_b32 s93, 0x79000
	s_mov_b32 s94, 0x7e000
	s_mov_b32 s95, 0x84000
	s_mov_b32 s96, 0x89000
	s_mov_b32 s97, 0x8f000
	s_mov_b32 s28, 0x94000
	s_mov_b32 s29, 0x9a000
	s_mov_b64 s[38:39], 0
	s_branch .LBB0_24
